# P7 GLU epilogue rewritten by hand: bias loaded once per tile and pre-scaled, yg tiles loaded two units ahead, packed f32 math, row reduction by v_permlane32/16_swap instead of LDS bpermutes
# baseline (speedup 1.0000x reference)
.LBB0_254:
	v_bfe_u32 v149, v192, 4, 2
	v_lshrrev_b32_e32 v142, 1, v192
	v_and_b32_e32 v142, 0x60, v142
	v_lshlrev_b32_e32 v143, 3, v149
	s_lshl_b32 s11, s57, 8
	v_readlane_b32 s72, v255, 11
	v_or3_b32 v144, v142, s11, v143
	v_readlane_b32 s73, v255, 12
	v_ashrrev_i32_e32 v145, 31, v144
	s_lshl_b32 s11, s56, 8
	v_ashrrev_i32_e32 v147, 2, v192
	v_lshl_add_u64 v[142:143], v[144:145], 2, s[72:73]
	global_load_dwordx4 v[176:179], v[142:143], off
	global_load_dwordx4 v[180:183], v[142:143], off offset:16
	global_load_dwordx4 v[184:187], v[142:143], off offset:512
	global_load_dwordx4 v[188:191], v[142:143], off offset:528
	v_and_or_b32 v146, v192, 15, s11
	v_and_b32_e32 v147, 0xffffffc0, v147
	v_add_u32_e32 v146, v146, v147
	v_ashrrev_i32_e32 v147, 31, v146
	v_lshlrev_b64 v[150:151], 10, v[146:147]
	v_lshlrev_b64 v[144:145], 1, v[144:145]
	v_lshl_add_u64 v[150:151], s[94:95], 0, v[150:151]
	v_lshl_add_u64 v[150:151], v[150:151], 0, v[144:145]
	global_load_dwordx4 v[204:207], v[150:151], off
	global_load_dwordx4 v[214:217], v[150:151], off offset:256
	v_readlane_b32 s48, v253, 7
	v_lshlrev_b64 v[160:161], 11, v[146:147]
	v_readlane_b32 s49, v253, 8
	v_lshl_add_u64 v[160:161], s[88:89], 0, v[160:161]
	v_lshl_add_u64 v[160:161], v[160:161], 0, v[144:145]
	v_lshl_add_u64 v[162:163], v[146:147], 2, s[48:49]
	v_cmp_eq_u32_e64 s[46:47], 0, v149
	v_mov_b32_e32 v164, 0xbfb8aa3b
	v_readlane_b32 s74, v255, 13
	v_readlane_b32 s75, v255, 14
	s_waitcnt vmcnt(2)
	v_pk_mul_f32 v[176:177], v[176:177], v[164:165] op_sel_hi:[1,0]
	v_pk_mul_f32 v[178:179], v[178:179], v[164:165] op_sel_hi:[1,0]
	v_pk_mul_f32 v[180:181], v[180:181], v[164:165] op_sel_hi:[1,0]
	v_pk_mul_f32 v[182:183], v[182:183], v[164:165] op_sel_hi:[1,0]
	v_pk_mul_f32 v[184:185], v[184:185], v[164:165] op_sel_hi:[1,0]
	v_pk_mul_f32 v[186:187], v[186:187], v[164:165] op_sel_hi:[1,0]
	v_pk_mul_f32 v[188:189], v[188:189], v[164:165] op_sel_hi:[1,0]
	v_pk_mul_f32 v[190:191], v[190:191], v[164:165] op_sel_hi:[1,0]
	s_mov_b64 vcc, 0x4000
	s_nop 0
	v_lshl_add_u64 v[150:151], v[150:151], 0, vcc
	global_load_dwordx4 v[218:221], v[150:151], off
	s_waitcnt vmcnt(2)
	v_pk_fma_f32 v[166:167], v[126:127], v[164:165], v[176:177] op_sel_hi:[1,0,1]
	v_pk_fma_f32 v[168:169], v[128:129], v[164:165], v[178:179] op_sel_hi:[1,0,1]
	v_pk_fma_f32 v[170:171], v[122:123], v[164:165], v[180:181] op_sel_hi:[1,0,1]
	v_pk_fma_f32 v[172:173], v[124:125], v[164:165], v[182:183] op_sel_hi:[1,0,1]
	v_exp_f32_e32 v166, v166
	v_exp_f32_e32 v167, v167
	v_exp_f32_e32 v168, v168
	v_exp_f32_e32 v169, v169
	v_exp_f32_e32 v170, v170
	v_exp_f32_e32 v171, v171
	v_exp_f32_e32 v172, v172
	v_exp_f32_e32 v173, v173
	v_lshlrev_b32_e32 v222, 16, v204
	v_and_b32_e32 v223, 0xffff0000, v204
	v_lshlrev_b32_e32 v224, 16, v205
	v_and_b32_e32 v225, 0xffff0000, v205
	v_lshlrev_b32_e32 v226, 16, v206
	v_and_b32_e32 v227, 0xffff0000, v206
	v_lshlrev_b32_e32 v228, 16, v207
	v_and_b32_e32 v229, 0xffff0000, v207
	v_pk_add_f32 v[166:167], v[166:167], 1.0 op_sel_hi:[1,0]
	v_pk_add_f32 v[168:169], v[168:169], 1.0 op_sel_hi:[1,0]
	v_pk_add_f32 v[170:171], v[170:171], 1.0 op_sel_hi:[1,0]
	v_pk_add_f32 v[172:173], v[172:173], 1.0 op_sel_hi:[1,0]
	v_rcp_f32_e32 v166, v166
	v_rcp_f32_e32 v167, v167
	v_rcp_f32_e32 v168, v168
	v_rcp_f32_e32 v169, v169
	v_rcp_f32_e32 v170, v170
	v_rcp_f32_e32 v171, v171
	v_rcp_f32_e32 v172, v172
	v_rcp_f32_e32 v173, v173
	s_nop 0
	v_pk_mul_f32 v[166:167], v[166:167], v[222:223]
	v_pk_mul_f32 v[168:169], v[168:169], v[224:225]
	v_pk_mul_f32 v[170:171], v[170:171], v[226:227]
	v_pk_mul_f32 v[172:173], v[172:173], v[228:229]
	v_pk_mul_f32 v[174:175], v[166:167], v[166:167]
	v_pk_fma_f32 v[174:175], v[168:169], v[168:169], v[174:175]
	v_pk_fma_f32 v[174:175], v[170:171], v[170:171], v[174:175]
	v_pk_fma_f32 v[174:175], v[172:173], v[172:173], v[174:175]
	v_cvt_pk_bf16_f32 v230, v166, v167
	v_cvt_pk_bf16_f32 v231, v168, v169
	v_cvt_pk_bf16_f32 v232, v170, v171
	v_cvt_pk_bf16_f32 v233, v172, v173
	global_store_dwordx4 v[160:161], v[230:233], off
	s_nop 1
	global_load_dwordx4 v[204:207], v[150:151], off offset:256
	s_waitcnt vmcnt(3)
	v_pk_fma_f32 v[166:167], v[118:119], v[164:165], v[184:185] op_sel_hi:[1,0,1]
	v_pk_fma_f32 v[168:169], v[120:121], v[164:165], v[186:187] op_sel_hi:[1,0,1]
	v_pk_fma_f32 v[170:171], v[114:115], v[164:165], v[188:189] op_sel_hi:[1,0,1]
	v_pk_fma_f32 v[172:173], v[116:117], v[164:165], v[190:191] op_sel_hi:[1,0,1]
	v_exp_f32_e32 v166, v166
	v_exp_f32_e32 v167, v167
	v_exp_f32_e32 v168, v168
	v_exp_f32_e32 v169, v169
	v_exp_f32_e32 v170, v170
	v_exp_f32_e32 v171, v171
	v_exp_f32_e32 v172, v172
	v_exp_f32_e32 v173, v173
	v_lshlrev_b32_e32 v222, 16, v214
	v_and_b32_e32 v223, 0xffff0000, v214
	v_lshlrev_b32_e32 v224, 16, v215
	v_and_b32_e32 v225, 0xffff0000, v215
	v_lshlrev_b32_e32 v226, 16, v216
	v_and_b32_e32 v227, 0xffff0000, v216
	v_lshlrev_b32_e32 v228, 16, v217
	v_and_b32_e32 v229, 0xffff0000, v217
	v_pk_add_f32 v[166:167], v[166:167], 1.0 op_sel_hi:[1,0]
	v_pk_add_f32 v[168:169], v[168:169], 1.0 op_sel_hi:[1,0]
	v_pk_add_f32 v[170:171], v[170:171], 1.0 op_sel_hi:[1,0]
	v_pk_add_f32 v[172:173], v[172:173], 1.0 op_sel_hi:[1,0]
	v_rcp_f32_e32 v166, v166
	v_rcp_f32_e32 v167, v167
	v_rcp_f32_e32 v168, v168
	v_rcp_f32_e32 v169, v169
	v_rcp_f32_e32 v170, v170
	v_rcp_f32_e32 v171, v171
	v_rcp_f32_e32 v172, v172
	v_rcp_f32_e32 v173, v173
	s_nop 0
	v_pk_mul_f32 v[166:167], v[166:167], v[222:223]
	v_pk_mul_f32 v[168:169], v[168:169], v[224:225]
	v_pk_mul_f32 v[170:171], v[170:171], v[226:227]
	v_pk_mul_f32 v[172:173], v[172:173], v[228:229]
	v_pk_fma_f32 v[174:175], v[166:167], v[166:167], v[174:175]
	v_pk_fma_f32 v[174:175], v[168:169], v[168:169], v[174:175]
	v_pk_fma_f32 v[174:175], v[170:171], v[170:171], v[174:175]
	v_pk_fma_f32 v[174:175], v[172:173], v[172:173], v[174:175]
	v_cvt_pk_bf16_f32 v230, v166, v167
	v_cvt_pk_bf16_f32 v231, v168, v169
	v_cvt_pk_bf16_f32 v232, v170, v171
	v_cvt_pk_bf16_f32 v233, v172, v173
	global_store_dwordx4 v[160:161], v[230:233], off offset:256
	v_add_f32_e32 v234, v174, v175
	v_mov_b32_e32 v235, v234
	s_nop 1
	v_permlane32_swap_b32 v235, v234
	s_nop 1
	v_add_f32_e32 v234, v234, v235
	v_mov_b32_e32 v235, v234
	s_nop 1
	v_permlane16_swap_b32 v235, v234
	s_nop 1
	v_add_f32_e32 v234, v234, v235
	s_mov_b64 exec, s[46:47]
	global_atomic_add_f32 v[162:163], v234, off
	s_mov_b64 exec, -1
	s_mov_b64 vcc, 0x8000
	s_nop 0
	v_lshl_add_u64 v[160:161], v[160:161], 0, vcc
	s_mov_b64 vcc, 0x4000
	s_nop 0
	v_lshl_add_u64 v[150:151], v[150:151], 0, vcc
	global_load_dwordx4 v[214:217], v[150:151], off
	s_waitcnt vmcnt(5)
	v_pk_fma_f32 v[166:167], v[110:111], v[164:165], v[176:177] op_sel_hi:[1,0,1]
	v_pk_fma_f32 v[168:169], v[112:113], v[164:165], v[178:179] op_sel_hi:[1,0,1]
	v_pk_fma_f32 v[170:171], v[106:107], v[164:165], v[180:181] op_sel_hi:[1,0,1]
	v_pk_fma_f32 v[172:173], v[108:109], v[164:165], v[182:183] op_sel_hi:[1,0,1]
	v_exp_f32_e32 v166, v166
	v_exp_f32_e32 v167, v167
	v_exp_f32_e32 v168, v168
	v_exp_f32_e32 v169, v169
	v_exp_f32_e32 v170, v170
	v_exp_f32_e32 v171, v171
	v_exp_f32_e32 v172, v172
	v_exp_f32_e32 v173, v173
	v_lshlrev_b32_e32 v222, 16, v218
	v_and_b32_e32 v223, 0xffff0000, v218
	v_lshlrev_b32_e32 v224, 16, v219
	v_and_b32_e32 v225, 0xffff0000, v219
	v_lshlrev_b32_e32 v226, 16, v220
	v_and_b32_e32 v227, 0xffff0000, v220
	v_lshlrev_b32_e32 v228, 16, v221
	v_and_b32_e32 v229, 0xffff0000, v221
	v_pk_add_f32 v[166:167], v[166:167], 1.0 op_sel_hi:[1,0]
	v_pk_add_f32 v[168:169], v[168:169], 1.0 op_sel_hi:[1,0]
	v_pk_add_f32 v[170:171], v[170:171], 1.0 op_sel_hi:[1,0]
	v_pk_add_f32 v[172:173], v[172:173], 1.0 op_sel_hi:[1,0]
	v_rcp_f32_e32 v166, v166
	v_rcp_f32_e32 v167, v167
	v_rcp_f32_e32 v168, v168
	v_rcp_f32_e32 v169, v169
	v_rcp_f32_e32 v170, v170
	v_rcp_f32_e32 v171, v171
	v_rcp_f32_e32 v172, v172
	v_rcp_f32_e32 v173, v173
	s_nop 0
	v_pk_mul_f32 v[166:167], v[166:167], v[222:223]
	v_pk_mul_f32 v[168:169], v[168:169], v[224:225]
	v_pk_mul_f32 v[170:171], v[170:171], v[226:227]
	v_pk_mul_f32 v[172:173], v[172:173], v[228:229]
	v_pk_mul_f32 v[174:175], v[166:167], v[166:167]
	v_pk_fma_f32 v[174:175], v[168:169], v[168:169], v[174:175]
	v_pk_fma_f32 v[174:175], v[170:171], v[170:171], v[174:175]
	v_pk_fma_f32 v[174:175], v[172:173], v[172:173], v[174:175]
	v_cvt_pk_bf16_f32 v230, v166, v167
	v_cvt_pk_bf16_f32 v231, v168, v169
	v_cvt_pk_bf16_f32 v232, v170, v171
	v_cvt_pk_bf16_f32 v233, v172, v173
	global_store_dwordx4 v[160:161], v[230:233], off
	s_nop 1
	global_load_dwordx4 v[218:221], v[150:151], off offset:256
	s_waitcnt vmcnt(5)
	v_pk_fma_f32 v[166:167], v[102:103], v[164:165], v[184:185] op_sel_hi:[1,0,1]
	v_pk_fma_f32 v[168:169], v[104:105], v[164:165], v[186:187] op_sel_hi:[1,0,1]
	v_pk_fma_f32 v[170:171], v[98:99], v[164:165], v[188:189] op_sel_hi:[1,0,1]
	v_pk_fma_f32 v[172:173], v[100:101], v[164:165], v[190:191] op_sel_hi:[1,0,1]
	v_exp_f32_e32 v166, v166
	v_exp_f32_e32 v167, v167
	v_exp_f32_e32 v168, v168
	v_exp_f32_e32 v169, v169
	v_exp_f32_e32 v170, v170
	v_exp_f32_e32 v171, v171
	v_exp_f32_e32 v172, v172
	v_exp_f32_e32 v173, v173
	v_lshlrev_b32_e32 v222, 16, v204
	v_and_b32_e32 v223, 0xffff0000, v204
	v_lshlrev_b32_e32 v224, 16, v205
	v_and_b32_e32 v225, 0xffff0000, v205
	v_lshlrev_b32_e32 v226, 16, v206
	v_and_b32_e32 v227, 0xffff0000, v206
	v_lshlrev_b32_e32 v228, 16, v207
	v_and_b32_e32 v229, 0xffff0000, v207
	v_pk_add_f32 v[166:167], v[166:167], 1.0 op_sel_hi:[1,0]
	v_pk_add_f32 v[168:169], v[168:169], 1.0 op_sel_hi:[1,0]
	v_pk_add_f32 v[170:171], v[170:171], 1.0 op_sel_hi:[1,0]
	v_pk_add_f32 v[172:173], v[172:173], 1.0 op_sel_hi:[1,0]
	v_rcp_f32_e32 v166, v166
	v_rcp_f32_e32 v167, v167
	v_rcp_f32_e32 v168, v168
	v_rcp_f32_e32 v169, v169
	v_rcp_f32_e32 v170, v170
	v_rcp_f32_e32 v171, v171
	v_rcp_f32_e32 v172, v172
	v_rcp_f32_e32 v173, v173
	s_nop 0
	v_pk_mul_f32 v[166:167], v[166:167], v[222:223]
	v_pk_mul_f32 v[168:169], v[168:169], v[224:225]
	v_pk_mul_f32 v[170:171], v[170:171], v[226:227]
	v_pk_mul_f32 v[172:173], v[172:173], v[228:229]
	v_pk_fma_f32 v[174:175], v[166:167], v[166:167], v[174:175]
	v_pk_fma_f32 v[174:175], v[168:169], v[168:169], v[174:175]
	v_pk_fma_f32 v[174:175], v[170:171], v[170:171], v[174:175]
	v_pk_fma_f32 v[174:175], v[172:173], v[172:173], v[174:175]
	v_cvt_pk_bf16_f32 v230, v166, v167
	v_cvt_pk_bf16_f32 v231, v168, v169
	v_cvt_pk_bf16_f32 v232, v170, v171
	v_cvt_pk_bf16_f32 v233, v172, v173
	global_store_dwordx4 v[160:161], v[230:233], off offset:256
	v_add_f32_e32 v234, v174, v175
	v_mov_b32_e32 v235, v234
	s_nop 1
	v_permlane32_swap_b32 v235, v234
	s_nop 1
	v_add_f32_e32 v234, v234, v235
	v_mov_b32_e32 v235, v234
	s_nop 1
	v_permlane16_swap_b32 v235, v234
	s_nop 1
	v_add_f32_e32 v234, v234, v235
	s_mov_b64 exec, s[46:47]
	global_atomic_add_f32 v[162:163], v234, off offset:64
	s_mov_b64 exec, -1
	s_mov_b64 vcc, 0x8000
	s_nop 0
	v_lshl_add_u64 v[160:161], v[160:161], 0, vcc
	s_mov_b64 vcc, 0x4000
	s_nop 0
	v_lshl_add_u64 v[150:151], v[150:151], 0, vcc
	global_load_dwordx4 v[204:207], v[150:151], off
	s_waitcnt vmcnt(5)
	v_pk_fma_f32 v[166:167], v[94:95], v[164:165], v[176:177] op_sel_hi:[1,0,1]
	v_pk_fma_f32 v[168:169], v[96:97], v[164:165], v[178:179] op_sel_hi:[1,0,1]
	v_pk_fma_f32 v[170:171], v[90:91], v[164:165], v[180:181] op_sel_hi:[1,0,1]
	v_pk_fma_f32 v[172:173], v[92:93], v[164:165], v[182:183] op_sel_hi:[1,0,1]
	v_exp_f32_e32 v166, v166
	v_exp_f32_e32 v167, v167
	v_exp_f32_e32 v168, v168
	v_exp_f32_e32 v169, v169
	v_exp_f32_e32 v170, v170
	v_exp_f32_e32 v171, v171
	v_exp_f32_e32 v172, v172
	v_exp_f32_e32 v173, v173
	v_lshlrev_b32_e32 v222, 16, v214
	v_and_b32_e32 v223, 0xffff0000, v214
	v_lshlrev_b32_e32 v224, 16, v215
	v_and_b32_e32 v225, 0xffff0000, v215
	v_lshlrev_b32_e32 v226, 16, v216
	v_and_b32_e32 v227, 0xffff0000, v216
	v_lshlrev_b32_e32 v228, 16, v217
	v_and_b32_e32 v229, 0xffff0000, v217
	v_pk_add_f32 v[166:167], v[166:167], 1.0 op_sel_hi:[1,0]
	v_pk_add_f32 v[168:169], v[168:169], 1.0 op_sel_hi:[1,0]
	v_pk_add_f32 v[170:171], v[170:171], 1.0 op_sel_hi:[1,0]
	v_pk_add_f32 v[172:173], v[172:173], 1.0 op_sel_hi:[1,0]
	v_rcp_f32_e32 v166, v166
	v_rcp_f32_e32 v167, v167
	v_rcp_f32_e32 v168, v168
	v_rcp_f32_e32 v169, v169
	v_rcp_f32_e32 v170, v170
	v_rcp_f32_e32 v171, v171
	v_rcp_f32_e32 v172, v172
	v_rcp_f32_e32 v173, v173
	s_nop 0
	v_pk_mul_f32 v[166:167], v[166:167], v[222:223]
	v_pk_mul_f32 v[168:169], v[168:169], v[224:225]
	v_pk_mul_f32 v[170:171], v[170:171], v[226:227]
	v_pk_mul_f32 v[172:173], v[172:173], v[228:229]
	v_pk_mul_f32 v[174:175], v[166:167], v[166:167]
	v_pk_fma_f32 v[174:175], v[168:169], v[168:169], v[174:175]
	v_pk_fma_f32 v[174:175], v[170:171], v[170:171], v[174:175]
	v_pk_fma_f32 v[174:175], v[172:173], v[172:173], v[174:175]
	v_cvt_pk_bf16_f32 v230, v166, v167
	v_cvt_pk_bf16_f32 v231, v168, v169
	v_cvt_pk_bf16_f32 v232, v170, v171
	v_cvt_pk_bf16_f32 v233, v172, v173
	global_store_dwordx4 v[160:161], v[230:233], off
	s_nop 1
	global_load_dwordx4 v[214:217], v[150:151], off offset:256
	s_waitcnt vmcnt(5)
	v_pk_fma_f32 v[166:167], v[86:87], v[164:165], v[184:185] op_sel_hi:[1,0,1]
	v_pk_fma_f32 v[168:169], v[88:89], v[164:165], v[186:187] op_sel_hi:[1,0,1]
	v_pk_fma_f32 v[170:171], v[82:83], v[164:165], v[188:189] op_sel_hi:[1,0,1]
	v_pk_fma_f32 v[172:173], v[84:85], v[164:165], v[190:191] op_sel_hi:[1,0,1]
	v_exp_f32_e32 v166, v166
	v_exp_f32_e32 v167, v167
	v_exp_f32_e32 v168, v168
	v_exp_f32_e32 v169, v169
	v_exp_f32_e32 v170, v170
	v_exp_f32_e32 v171, v171
	v_exp_f32_e32 v172, v172
	v_exp_f32_e32 v173, v173
	v_lshlrev_b32_e32 v222, 16, v218
	v_and_b32_e32 v223, 0xffff0000, v218
	v_lshlrev_b32_e32 v224, 16, v219
	v_and_b32_e32 v225, 0xffff0000, v219
	v_lshlrev_b32_e32 v226, 16, v220
	v_and_b32_e32 v227, 0xffff0000, v220
	v_lshlrev_b32_e32 v228, 16, v221
	v_and_b32_e32 v229, 0xffff0000, v221
	v_pk_add_f32 v[166:167], v[166:167], 1.0 op_sel_hi:[1,0]
	v_pk_add_f32 v[168:169], v[168:169], 1.0 op_sel_hi:[1,0]
	v_pk_add_f32 v[170:171], v[170:171], 1.0 op_sel_hi:[1,0]
	v_pk_add_f32 v[172:173], v[172:173], 1.0 op_sel_hi:[1,0]
	v_rcp_f32_e32 v166, v166
	v_rcp_f32_e32 v167, v167
	v_rcp_f32_e32 v168, v168
	v_rcp_f32_e32 v169, v169
	v_rcp_f32_e32 v170, v170
	v_rcp_f32_e32 v171, v171
	v_rcp_f32_e32 v172, v172
	v_rcp_f32_e32 v173, v173
	s_nop 0
	v_pk_mul_f32 v[166:167], v[166:167], v[222:223]
	v_pk_mul_f32 v[168:169], v[168:169], v[224:225]
	v_pk_mul_f32 v[170:171], v[170:171], v[226:227]
	v_pk_mul_f32 v[172:173], v[172:173], v[228:229]
	v_pk_fma_f32 v[174:175], v[166:167], v[166:167], v[174:175]
	v_pk_fma_f32 v[174:175], v[168:169], v[168:169], v[174:175]
	v_pk_fma_f32 v[174:175], v[170:171], v[170:171], v[174:175]
	v_pk_fma_f32 v[174:175], v[172:173], v[172:173], v[174:175]
	v_cvt_pk_bf16_f32 v230, v166, v167
	v_cvt_pk_bf16_f32 v231, v168, v169
	v_cvt_pk_bf16_f32 v232, v170, v171
	v_cvt_pk_bf16_f32 v233, v172, v173
	global_store_dwordx4 v[160:161], v[230:233], off offset:256
	v_add_f32_e32 v234, v174, v175
	v_mov_b32_e32 v235, v234
	s_nop 1
	v_permlane32_swap_b32 v235, v234
	s_nop 1
	v_add_f32_e32 v234, v234, v235
	v_mov_b32_e32 v235, v234
	s_nop 1
	v_permlane16_swap_b32 v235, v234
	s_nop 1
	v_add_f32_e32 v234, v234, v235
	s_mov_b64 exec, s[46:47]
	global_atomic_add_f32 v[162:163], v234, off offset:128
	s_mov_b64 exec, -1
	s_mov_b64 vcc, 0x8000
	s_nop 0
	v_lshl_add_u64 v[160:161], v[160:161], 0, vcc
	s_mov_b64 vcc, 0x14000
	s_nop 0
	v_lshl_add_u64 v[150:151], v[150:151], 0, vcc
	global_load_dwordx4 v[218:221], v[150:151], off
	s_waitcnt vmcnt(5)
	v_pk_fma_f32 v[166:167], v[76:77], v[164:165], v[176:177] op_sel_hi:[1,0,1]
	v_pk_fma_f32 v[168:169], v[78:79], v[164:165], v[178:179] op_sel_hi:[1,0,1]
	v_pk_fma_f32 v[170:171], v[72:73], v[164:165], v[180:181] op_sel_hi:[1,0,1]
	v_pk_fma_f32 v[172:173], v[74:75], v[164:165], v[182:183] op_sel_hi:[1,0,1]
	v_exp_f32_e32 v166, v166
	v_exp_f32_e32 v167, v167
	v_exp_f32_e32 v168, v168
	v_exp_f32_e32 v169, v169
	v_exp_f32_e32 v170, v170
	v_exp_f32_e32 v171, v171
	v_exp_f32_e32 v172, v172
	v_exp_f32_e32 v173, v173
	v_lshlrev_b32_e32 v222, 16, v204
	v_and_b32_e32 v223, 0xffff0000, v204
	v_lshlrev_b32_e32 v224, 16, v205
	v_and_b32_e32 v225, 0xffff0000, v205
	v_lshlrev_b32_e32 v226, 16, v206
	v_and_b32_e32 v227, 0xffff0000, v206
	v_lshlrev_b32_e32 v228, 16, v207
	v_and_b32_e32 v229, 0xffff0000, v207
	v_pk_add_f32 v[166:167], v[166:167], 1.0 op_sel_hi:[1,0]
	v_pk_add_f32 v[168:169], v[168:169], 1.0 op_sel_hi:[1,0]
	v_pk_add_f32 v[170:171], v[170:171], 1.0 op_sel_hi:[1,0]
	v_pk_add_f32 v[172:173], v[172:173], 1.0 op_sel_hi:[1,0]
	v_rcp_f32_e32 v166, v166
	v_rcp_f32_e32 v167, v167
	v_rcp_f32_e32 v168, v168
	v_rcp_f32_e32 v169, v169
	v_rcp_f32_e32 v170, v170
	v_rcp_f32_e32 v171, v171
	v_rcp_f32_e32 v172, v172
	v_rcp_f32_e32 v173, v173
	s_nop 0
	v_pk_mul_f32 v[166:167], v[166:167], v[222:223]
	v_pk_mul_f32 v[168:169], v[168:169], v[224:225]
	v_pk_mul_f32 v[170:171], v[170:171], v[226:227]
	v_pk_mul_f32 v[172:173], v[172:173], v[228:229]
	v_pk_mul_f32 v[174:175], v[166:167], v[166:167]
	v_pk_fma_f32 v[174:175], v[168:169], v[168:169], v[174:175]
	v_pk_fma_f32 v[174:175], v[170:171], v[170:171], v[174:175]
	v_pk_fma_f32 v[174:175], v[172:173], v[172:173], v[174:175]
	v_cvt_pk_bf16_f32 v230, v166, v167
	v_cvt_pk_bf16_f32 v231, v168, v169
	v_cvt_pk_bf16_f32 v232, v170, v171
	v_cvt_pk_bf16_f32 v233, v172, v173
	global_store_dwordx4 v[160:161], v[230:233], off
	s_nop 1
	global_load_dwordx4 v[204:207], v[150:151], off offset:256
	s_waitcnt vmcnt(5)
	v_pk_fma_f32 v[166:167], v[68:69], v[164:165], v[184:185] op_sel_hi:[1,0,1]
	v_pk_fma_f32 v[168:169], v[70:71], v[164:165], v[186:187] op_sel_hi:[1,0,1]
	v_pk_fma_f32 v[170:171], v[64:65], v[164:165], v[188:189] op_sel_hi:[1,0,1]
	v_pk_fma_f32 v[172:173], v[66:67], v[164:165], v[190:191] op_sel_hi:[1,0,1]
	v_exp_f32_e32 v166, v166
	v_exp_f32_e32 v167, v167
	v_exp_f32_e32 v168, v168
	v_exp_f32_e32 v169, v169
	v_exp_f32_e32 v170, v170
	v_exp_f32_e32 v171, v171
	v_exp_f32_e32 v172, v172
	v_exp_f32_e32 v173, v173
	v_lshlrev_b32_e32 v222, 16, v214
	v_and_b32_e32 v223, 0xffff0000, v214
	v_lshlrev_b32_e32 v224, 16, v215
	v_and_b32_e32 v225, 0xffff0000, v215
	v_lshlrev_b32_e32 v226, 16, v216
	v_and_b32_e32 v227, 0xffff0000, v216
	v_lshlrev_b32_e32 v228, 16, v217
	v_and_b32_e32 v229, 0xffff0000, v217
	v_pk_add_f32 v[166:167], v[166:167], 1.0 op_sel_hi:[1,0]
	v_pk_add_f32 v[168:169], v[168:169], 1.0 op_sel_hi:[1,0]
	v_pk_add_f32 v[170:171], v[170:171], 1.0 op_sel_hi:[1,0]
	v_pk_add_f32 v[172:173], v[172:173], 1.0 op_sel_hi:[1,0]
	v_rcp_f32_e32 v166, v166
	v_rcp_f32_e32 v167, v167
	v_rcp_f32_e32 v168, v168
	v_rcp_f32_e32 v169, v169
	v_rcp_f32_e32 v170, v170
	v_rcp_f32_e32 v171, v171
	v_rcp_f32_e32 v172, v172
	v_rcp_f32_e32 v173, v173
	s_nop 0
	v_pk_mul_f32 v[166:167], v[166:167], v[222:223]
	v_pk_mul_f32 v[168:169], v[168:169], v[224:225]
	v_pk_mul_f32 v[170:171], v[170:171], v[226:227]
	v_pk_mul_f32 v[172:173], v[172:173], v[228:229]
	v_pk_fma_f32 v[174:175], v[166:167], v[166:167], v[174:175]
	v_pk_fma_f32 v[174:175], v[168:169], v[168:169], v[174:175]
	v_pk_fma_f32 v[174:175], v[170:171], v[170:171], v[174:175]
	v_pk_fma_f32 v[174:175], v[172:173], v[172:173], v[174:175]
	v_cvt_pk_bf16_f32 v230, v166, v167
	v_cvt_pk_bf16_f32 v231, v168, v169
	v_cvt_pk_bf16_f32 v232, v170, v171
	v_cvt_pk_bf16_f32 v233, v172, v173
	global_store_dwordx4 v[160:161], v[230:233], off offset:256
	v_add_f32_e32 v234, v174, v175
	v_mov_b32_e32 v235, v234
	s_nop 1
	v_permlane32_swap_b32 v235, v234
	s_nop 1
	v_add_f32_e32 v234, v234, v235
	v_mov_b32_e32 v235, v234
	s_nop 1
	v_permlane16_swap_b32 v235, v234
	s_nop 1
	v_add_f32_e32 v234, v234, v235
	s_mov_b64 exec, s[46:47]
	global_atomic_add_f32 v[162:163], v234, off offset:192
	s_mov_b64 exec, -1
	s_mov_b64 vcc, 0x28000
	s_nop 0
	v_lshl_add_u64 v[160:161], v[160:161], 0, vcc
	s_mov_b64 vcc, 0x4000
	s_nop 0
	v_lshl_add_u64 v[150:151], v[150:151], 0, vcc
	global_load_dwordx4 v[214:217], v[150:151], off
	s_waitcnt vmcnt(5)
	v_pk_fma_f32 v[166:167], v[60:61], v[164:165], v[176:177] op_sel_hi:[1,0,1]
	v_pk_fma_f32 v[168:169], v[62:63], v[164:165], v[178:179] op_sel_hi:[1,0,1]
	v_pk_fma_f32 v[170:171], v[56:57], v[164:165], v[180:181] op_sel_hi:[1,0,1]
	v_pk_fma_f32 v[172:173], v[58:59], v[164:165], v[182:183] op_sel_hi:[1,0,1]
	v_exp_f32_e32 v166, v166
	v_exp_f32_e32 v167, v167
	v_exp_f32_e32 v168, v168
	v_exp_f32_e32 v169, v169
	v_exp_f32_e32 v170, v170
	v_exp_f32_e32 v171, v171
	v_exp_f32_e32 v172, v172
	v_exp_f32_e32 v173, v173
	v_lshlrev_b32_e32 v222, 16, v218
	v_and_b32_e32 v223, 0xffff0000, v218
	v_lshlrev_b32_e32 v224, 16, v219
	v_and_b32_e32 v225, 0xffff0000, v219
	v_lshlrev_b32_e32 v226, 16, v220
	v_and_b32_e32 v227, 0xffff0000, v220
	v_lshlrev_b32_e32 v228, 16, v221
	v_and_b32_e32 v229, 0xffff0000, v221
	v_pk_add_f32 v[166:167], v[166:167], 1.0 op_sel_hi:[1,0]
	v_pk_add_f32 v[168:169], v[168:169], 1.0 op_sel_hi:[1,0]
	v_pk_add_f32 v[170:171], v[170:171], 1.0 op_sel_hi:[1,0]
	v_pk_add_f32 v[172:173], v[172:173], 1.0 op_sel_hi:[1,0]
	v_rcp_f32_e32 v166, v166
	v_rcp_f32_e32 v167, v167
	v_rcp_f32_e32 v168, v168
	v_rcp_f32_e32 v169, v169
	v_rcp_f32_e32 v170, v170
	v_rcp_f32_e32 v171, v171
	v_rcp_f32_e32 v172, v172
	v_rcp_f32_e32 v173, v173
	s_nop 0
	v_pk_mul_f32 v[166:167], v[166:167], v[222:223]
	v_pk_mul_f32 v[168:169], v[168:169], v[224:225]
	v_pk_mul_f32 v[170:171], v[170:171], v[226:227]
	v_pk_mul_f32 v[172:173], v[172:173], v[228:229]
	v_pk_mul_f32 v[174:175], v[166:167], v[166:167]
	v_pk_fma_f32 v[174:175], v[168:169], v[168:169], v[174:175]
	v_pk_fma_f32 v[174:175], v[170:171], v[170:171], v[174:175]
	v_pk_fma_f32 v[174:175], v[172:173], v[172:173], v[174:175]
	v_cvt_pk_bf16_f32 v230, v166, v167
	v_cvt_pk_bf16_f32 v231, v168, v169
	v_cvt_pk_bf16_f32 v232, v170, v171
	v_cvt_pk_bf16_f32 v233, v172, v173
	global_store_dwordx4 v[160:161], v[230:233], off
	s_nop 1
	global_load_dwordx4 v[218:221], v[150:151], off offset:256
	s_waitcnt vmcnt(5)
	v_pk_fma_f32 v[166:167], v[52:53], v[164:165], v[184:185] op_sel_hi:[1,0,1]
	v_pk_fma_f32 v[168:169], v[54:55], v[164:165], v[186:187] op_sel_hi:[1,0,1]
	v_pk_fma_f32 v[170:171], v[48:49], v[164:165], v[188:189] op_sel_hi:[1,0,1]
	v_pk_fma_f32 v[172:173], v[50:51], v[164:165], v[190:191] op_sel_hi:[1,0,1]
	v_exp_f32_e32 v166, v166
	v_exp_f32_e32 v167, v167
	v_exp_f32_e32 v168, v168
	v_exp_f32_e32 v169, v169
	v_exp_f32_e32 v170, v170
	v_exp_f32_e32 v171, v171
	v_exp_f32_e32 v172, v172
	v_exp_f32_e32 v173, v173
	v_lshlrev_b32_e32 v222, 16, v204
	v_and_b32_e32 v223, 0xffff0000, v204
	v_lshlrev_b32_e32 v224, 16, v205
	v_and_b32_e32 v225, 0xffff0000, v205
	v_lshlrev_b32_e32 v226, 16, v206
	v_and_b32_e32 v227, 0xffff0000, v206
	v_lshlrev_b32_e32 v228, 16, v207
	v_and_b32_e32 v229, 0xffff0000, v207
	v_pk_add_f32 v[166:167], v[166:167], 1.0 op_sel_hi:[1,0]
	v_pk_add_f32 v[168:169], v[168:169], 1.0 op_sel_hi:[1,0]
	v_pk_add_f32 v[170:171], v[170:171], 1.0 op_sel_hi:[1,0]
	v_pk_add_f32 v[172:173], v[172:173], 1.0 op_sel_hi:[1,0]
	v_rcp_f32_e32 v166, v166
	v_rcp_f32_e32 v167, v167
	v_rcp_f32_e32 v168, v168
	v_rcp_f32_e32 v169, v169
	v_rcp_f32_e32 v170, v170
	v_rcp_f32_e32 v171, v171
	v_rcp_f32_e32 v172, v172
	v_rcp_f32_e32 v173, v173
	s_nop 0
	v_pk_mul_f32 v[166:167], v[166:167], v[222:223]
	v_pk_mul_f32 v[168:169], v[168:169], v[224:225]
	v_pk_mul_f32 v[170:171], v[170:171], v[226:227]
	v_pk_mul_f32 v[172:173], v[172:173], v[228:229]
	v_pk_fma_f32 v[174:175], v[166:167], v[166:167], v[174:175]
	v_pk_fma_f32 v[174:175], v[168:169], v[168:169], v[174:175]
	v_pk_fma_f32 v[174:175], v[170:171], v[170:171], v[174:175]
	v_pk_fma_f32 v[174:175], v[172:173], v[172:173], v[174:175]
	v_cvt_pk_bf16_f32 v230, v166, v167
	v_cvt_pk_bf16_f32 v231, v168, v169
	v_cvt_pk_bf16_f32 v232, v170, v171
	v_cvt_pk_bf16_f32 v233, v172, v173
	global_store_dwordx4 v[160:161], v[230:233], off offset:256
	v_add_f32_e32 v234, v174, v175
	v_mov_b32_e32 v235, v234
	s_nop 1
	v_permlane32_swap_b32 v235, v234
	s_nop 1
	v_add_f32_e32 v234, v234, v235
	v_mov_b32_e32 v235, v234
	s_nop 1
	v_permlane16_swap_b32 v235, v234
	s_nop 1
	v_add_f32_e32 v234, v234, v235
	s_mov_b64 exec, s[46:47]
	global_atomic_add_f32 v[162:163], v234, off offset:512
	s_mov_b64 exec, -1
	s_mov_b64 vcc, 0x8000
	s_nop 0
	v_lshl_add_u64 v[160:161], v[160:161], 0, vcc
	s_mov_b64 vcc, 0x4000
	s_nop 0
	v_lshl_add_u64 v[150:151], v[150:151], 0, vcc
	global_load_dwordx4 v[204:207], v[150:151], off
	s_waitcnt vmcnt(5)
	v_pk_fma_f32 v[166:167], v[44:45], v[164:165], v[176:177] op_sel_hi:[1,0,1]
	v_pk_fma_f32 v[168:169], v[46:47], v[164:165], v[178:179] op_sel_hi:[1,0,1]
	v_pk_fma_f32 v[170:171], v[40:41], v[164:165], v[180:181] op_sel_hi:[1,0,1]
	v_pk_fma_f32 v[172:173], v[42:43], v[164:165], v[182:183] op_sel_hi:[1,0,1]
	v_exp_f32_e32 v166, v166
	v_exp_f32_e32 v167, v167
	v_exp_f32_e32 v168, v168
	v_exp_f32_e32 v169, v169
	v_exp_f32_e32 v170, v170
	v_exp_f32_e32 v171, v171
	v_exp_f32_e32 v172, v172
	v_exp_f32_e32 v173, v173
	v_lshlrev_b32_e32 v222, 16, v214
	v_and_b32_e32 v223, 0xffff0000, v214
	v_lshlrev_b32_e32 v224, 16, v215
	v_and_b32_e32 v225, 0xffff0000, v215
	v_lshlrev_b32_e32 v226, 16, v216
	v_and_b32_e32 v227, 0xffff0000, v216
	v_lshlrev_b32_e32 v228, 16, v217
	v_and_b32_e32 v229, 0xffff0000, v217
	v_pk_add_f32 v[166:167], v[166:167], 1.0 op_sel_hi:[1,0]
	v_pk_add_f32 v[168:169], v[168:169], 1.0 op_sel_hi:[1,0]
	v_pk_add_f32 v[170:171], v[170:171], 1.0 op_sel_hi:[1,0]
	v_pk_add_f32 v[172:173], v[172:173], 1.0 op_sel_hi:[1,0]
	v_rcp_f32_e32 v166, v166
	v_rcp_f32_e32 v167, v167
	v_rcp_f32_e32 v168, v168
	v_rcp_f32_e32 v169, v169
	v_rcp_f32_e32 v170, v170
	v_rcp_f32_e32 v171, v171
	v_rcp_f32_e32 v172, v172
	v_rcp_f32_e32 v173, v173
	s_nop 0
	v_pk_mul_f32 v[166:167], v[166:167], v[222:223]
	v_pk_mul_f32 v[168:169], v[168:169], v[224:225]
	v_pk_mul_f32 v[170:171], v[170:171], v[226:227]
	v_pk_mul_f32 v[172:173], v[172:173], v[228:229]
	v_pk_mul_f32 v[174:175], v[166:167], v[166:167]
	v_pk_fma_f32 v[174:175], v[168:169], v[168:169], v[174:175]
	v_pk_fma_f32 v[174:175], v[170:171], v[170:171], v[174:175]
	v_pk_fma_f32 v[174:175], v[172:173], v[172:173], v[174:175]
	v_cvt_pk_bf16_f32 v230, v166, v167
	v_cvt_pk_bf16_f32 v231, v168, v169
	v_cvt_pk_bf16_f32 v232, v170, v171
	v_cvt_pk_bf16_f32 v233, v172, v173
	global_store_dwordx4 v[160:161], v[230:233], off
	s_nop 1
	global_load_dwordx4 v[214:217], v[150:151], off offset:256
	s_waitcnt vmcnt(5)
	v_pk_fma_f32 v[166:167], v[36:37], v[164:165], v[184:185] op_sel_hi:[1,0,1]
	v_pk_fma_f32 v[168:169], v[38:39], v[164:165], v[186:187] op_sel_hi:[1,0,1]
	v_pk_fma_f32 v[170:171], v[32:33], v[164:165], v[188:189] op_sel_hi:[1,0,1]
	v_pk_fma_f32 v[172:173], v[34:35], v[164:165], v[190:191] op_sel_hi:[1,0,1]
	v_exp_f32_e32 v166, v166
	v_exp_f32_e32 v167, v167
	v_exp_f32_e32 v168, v168
	v_exp_f32_e32 v169, v169
	v_exp_f32_e32 v170, v170
	v_exp_f32_e32 v171, v171
	v_exp_f32_e32 v172, v172
	v_exp_f32_e32 v173, v173
	v_lshlrev_b32_e32 v222, 16, v218
	v_and_b32_e32 v223, 0xffff0000, v218
	v_lshlrev_b32_e32 v224, 16, v219
	v_and_b32_e32 v225, 0xffff0000, v219
	v_lshlrev_b32_e32 v226, 16, v220
	v_and_b32_e32 v227, 0xffff0000, v220
	v_lshlrev_b32_e32 v228, 16, v221
	v_and_b32_e32 v229, 0xffff0000, v221
	v_pk_add_f32 v[166:167], v[166:167], 1.0 op_sel_hi:[1,0]
	v_pk_add_f32 v[168:169], v[168:169], 1.0 op_sel_hi:[1,0]
	v_pk_add_f32 v[170:171], v[170:171], 1.0 op_sel_hi:[1,0]
	v_pk_add_f32 v[172:173], v[172:173], 1.0 op_sel_hi:[1,0]
	v_rcp_f32_e32 v166, v166
	v_rcp_f32_e32 v167, v167
	v_rcp_f32_e32 v168, v168
	v_rcp_f32_e32 v169, v169
	v_rcp_f32_e32 v170, v170
	v_rcp_f32_e32 v171, v171
	v_rcp_f32_e32 v172, v172
	v_rcp_f32_e32 v173, v173
	s_nop 0
	v_pk_mul_f32 v[166:167], v[166:167], v[222:223]
	v_pk_mul_f32 v[168:169], v[168:169], v[224:225]
	v_pk_mul_f32 v[170:171], v[170:171], v[226:227]
	v_pk_mul_f32 v[172:173], v[172:173], v[228:229]
	v_pk_fma_f32 v[174:175], v[166:167], v[166:167], v[174:175]
	v_pk_fma_f32 v[174:175], v[168:169], v[168:169], v[174:175]
	v_pk_fma_f32 v[174:175], v[170:171], v[170:171], v[174:175]
	v_pk_fma_f32 v[174:175], v[172:173], v[172:173], v[174:175]
	v_cvt_pk_bf16_f32 v230, v166, v167
	v_cvt_pk_bf16_f32 v231, v168, v169
	v_cvt_pk_bf16_f32 v232, v170, v171
	v_cvt_pk_bf16_f32 v233, v172, v173
	global_store_dwordx4 v[160:161], v[230:233], off offset:256
	v_add_f32_e32 v234, v174, v175
	v_mov_b32_e32 v235, v234
	s_nop 1
	v_permlane32_swap_b32 v235, v234
	s_nop 1
	v_add_f32_e32 v234, v234, v235
	v_mov_b32_e32 v235, v234
	s_nop 1
	v_permlane16_swap_b32 v235, v234
	s_nop 1
	v_add_f32_e32 v234, v234, v235
	s_mov_b64 exec, s[46:47]
	global_atomic_add_f32 v[162:163], v234, off offset:576
	s_mov_b64 exec, -1
	s_mov_b64 vcc, 0x8000
	s_nop 0
	v_lshl_add_u64 v[160:161], v[160:161], 0, vcc
	s_mov_b64 vcc, 0x4000
	s_nop 0
	v_lshl_add_u64 v[150:151], v[150:151], 0, vcc
	global_load_dwordx4 v[218:221], v[150:151], off
	s_waitcnt vmcnt(5)
	v_pk_fma_f32 v[166:167], v[28:29], v[164:165], v[176:177] op_sel_hi:[1,0,1]
	v_pk_fma_f32 v[168:169], v[30:31], v[164:165], v[178:179] op_sel_hi:[1,0,1]
	v_pk_fma_f32 v[170:171], v[24:25], v[164:165], v[180:181] op_sel_hi:[1,0,1]
	v_pk_fma_f32 v[172:173], v[26:27], v[164:165], v[182:183] op_sel_hi:[1,0,1]
	v_exp_f32_e32 v166, v166
	v_exp_f32_e32 v167, v167
	v_exp_f32_e32 v168, v168
	v_exp_f32_e32 v169, v169
	v_exp_f32_e32 v170, v170
	v_exp_f32_e32 v171, v171
	v_exp_f32_e32 v172, v172
	v_exp_f32_e32 v173, v173
	v_lshlrev_b32_e32 v222, 16, v204
	v_and_b32_e32 v223, 0xffff0000, v204
	v_lshlrev_b32_e32 v224, 16, v205
	v_and_b32_e32 v225, 0xffff0000, v205
	v_lshlrev_b32_e32 v226, 16, v206
	v_and_b32_e32 v227, 0xffff0000, v206
	v_lshlrev_b32_e32 v228, 16, v207
	v_and_b32_e32 v229, 0xffff0000, v207
	v_pk_add_f32 v[166:167], v[166:167], 1.0 op_sel_hi:[1,0]
	v_pk_add_f32 v[168:169], v[168:169], 1.0 op_sel_hi:[1,0]
	v_pk_add_f32 v[170:171], v[170:171], 1.0 op_sel_hi:[1,0]
	v_pk_add_f32 v[172:173], v[172:173], 1.0 op_sel_hi:[1,0]
	v_rcp_f32_e32 v166, v166
	v_rcp_f32_e32 v167, v167
	v_rcp_f32_e32 v168, v168
	v_rcp_f32_e32 v169, v169
	v_rcp_f32_e32 v170, v170
	v_rcp_f32_e32 v171, v171
	v_rcp_f32_e32 v172, v172
	v_rcp_f32_e32 v173, v173
	s_nop 0
	v_pk_mul_f32 v[166:167], v[166:167], v[222:223]
	v_pk_mul_f32 v[168:169], v[168:169], v[224:225]
	v_pk_mul_f32 v[170:171], v[170:171], v[226:227]
	v_pk_mul_f32 v[172:173], v[172:173], v[228:229]
	v_pk_mul_f32 v[174:175], v[166:167], v[166:167]
	v_pk_fma_f32 v[174:175], v[168:169], v[168:169], v[174:175]
	v_pk_fma_f32 v[174:175], v[170:171], v[170:171], v[174:175]
	v_pk_fma_f32 v[174:175], v[172:173], v[172:173], v[174:175]
	v_cvt_pk_bf16_f32 v230, v166, v167
	v_cvt_pk_bf16_f32 v231, v168, v169
	v_cvt_pk_bf16_f32 v232, v170, v171
	v_cvt_pk_bf16_f32 v233, v172, v173
	global_store_dwordx4 v[160:161], v[230:233], off
	s_nop 1
	global_load_dwordx4 v[204:207], v[150:151], off offset:256
	s_waitcnt vmcnt(5)
	v_pk_fma_f32 v[166:167], v[20:21], v[164:165], v[184:185] op_sel_hi:[1,0,1]
	v_pk_fma_f32 v[168:169], v[22:23], v[164:165], v[186:187] op_sel_hi:[1,0,1]
	v_pk_fma_f32 v[170:171], v[16:17], v[164:165], v[188:189] op_sel_hi:[1,0,1]
	v_pk_fma_f32 v[172:173], v[18:19], v[164:165], v[190:191] op_sel_hi:[1,0,1]
	v_exp_f32_e32 v166, v166
	v_exp_f32_e32 v167, v167
	v_exp_f32_e32 v168, v168
	v_exp_f32_e32 v169, v169
	v_exp_f32_e32 v170, v170
	v_exp_f32_e32 v171, v171
	v_exp_f32_e32 v172, v172
	v_exp_f32_e32 v173, v173
	v_lshlrev_b32_e32 v222, 16, v214
	v_and_b32_e32 v223, 0xffff0000, v214
	v_lshlrev_b32_e32 v224, 16, v215
	v_and_b32_e32 v225, 0xffff0000, v215
	v_lshlrev_b32_e32 v226, 16, v216
	v_and_b32_e32 v227, 0xffff0000, v216
	v_lshlrev_b32_e32 v228, 16, v217
	v_and_b32_e32 v229, 0xffff0000, v217
	v_pk_add_f32 v[166:167], v[166:167], 1.0 op_sel_hi:[1,0]
	v_pk_add_f32 v[168:169], v[168:169], 1.0 op_sel_hi:[1,0]
	v_pk_add_f32 v[170:171], v[170:171], 1.0 op_sel_hi:[1,0]
	v_pk_add_f32 v[172:173], v[172:173], 1.0 op_sel_hi:[1,0]
	v_rcp_f32_e32 v166, v166
	v_rcp_f32_e32 v167, v167
	v_rcp_f32_e32 v168, v168
	v_rcp_f32_e32 v169, v169
	v_rcp_f32_e32 v170, v170
	v_rcp_f32_e32 v171, v171
	v_rcp_f32_e32 v172, v172
	v_rcp_f32_e32 v173, v173
	s_nop 0
	v_pk_mul_f32 v[166:167], v[166:167], v[222:223]
	v_pk_mul_f32 v[168:169], v[168:169], v[224:225]
	v_pk_mul_f32 v[170:171], v[170:171], v[226:227]
	v_pk_mul_f32 v[172:173], v[172:173], v[228:229]
	v_pk_fma_f32 v[174:175], v[166:167], v[166:167], v[174:175]
	v_pk_fma_f32 v[174:175], v[168:169], v[168:169], v[174:175]
	v_pk_fma_f32 v[174:175], v[170:171], v[170:171], v[174:175]
	v_pk_fma_f32 v[174:175], v[172:173], v[172:173], v[174:175]
	v_cvt_pk_bf16_f32 v230, v166, v167
	v_cvt_pk_bf16_f32 v231, v168, v169
	v_cvt_pk_bf16_f32 v232, v170, v171
	v_cvt_pk_bf16_f32 v233, v172, v173
	global_store_dwordx4 v[160:161], v[230:233], off offset:256
	v_add_f32_e32 v234, v174, v175
	v_mov_b32_e32 v235, v234
	s_nop 1
	v_permlane32_swap_b32 v235, v234
	s_nop 1
	v_add_f32_e32 v234, v234, v235
	v_mov_b32_e32 v235, v234
	s_nop 1
	v_permlane16_swap_b32 v235, v234
	s_nop 1
	v_add_f32_e32 v234, v234, v235
	s_mov_b64 exec, s[46:47]
	global_atomic_add_f32 v[162:163], v234, off offset:640
	s_mov_b64 exec, -1
	s_mov_b64 vcc, 0x8000
	s_nop 0
	v_lshl_add_u64 v[160:161], v[160:161], 0, vcc
	s_waitcnt vmcnt(4)
	v_pk_fma_f32 v[166:167], v[12:13], v[164:165], v[176:177] op_sel_hi:[1,0,1]
	v_pk_fma_f32 v[168:169], v[14:15], v[164:165], v[178:179] op_sel_hi:[1,0,1]
	v_pk_fma_f32 v[170:171], v[8:9], v[164:165], v[180:181] op_sel_hi:[1,0,1]
	v_pk_fma_f32 v[172:173], v[10:11], v[164:165], v[182:183] op_sel_hi:[1,0,1]
	v_exp_f32_e32 v166, v166
	v_exp_f32_e32 v167, v167
	v_exp_f32_e32 v168, v168
	v_exp_f32_e32 v169, v169
	v_exp_f32_e32 v170, v170
	v_exp_f32_e32 v171, v171
	v_exp_f32_e32 v172, v172
	v_exp_f32_e32 v173, v173
	v_lshlrev_b32_e32 v222, 16, v218
	v_and_b32_e32 v223, 0xffff0000, v218
	v_lshlrev_b32_e32 v224, 16, v219
	v_and_b32_e32 v225, 0xffff0000, v219
	v_lshlrev_b32_e32 v226, 16, v220
	v_and_b32_e32 v227, 0xffff0000, v220
	v_lshlrev_b32_e32 v228, 16, v221
	v_and_b32_e32 v229, 0xffff0000, v221
	v_pk_add_f32 v[166:167], v[166:167], 1.0 op_sel_hi:[1,0]
	v_pk_add_f32 v[168:169], v[168:169], 1.0 op_sel_hi:[1,0]
	v_pk_add_f32 v[170:171], v[170:171], 1.0 op_sel_hi:[1,0]
	v_pk_add_f32 v[172:173], v[172:173], 1.0 op_sel_hi:[1,0]
	v_rcp_f32_e32 v166, v166
	v_rcp_f32_e32 v167, v167
	v_rcp_f32_e32 v168, v168
	v_rcp_f32_e32 v169, v169
	v_rcp_f32_e32 v170, v170
	v_rcp_f32_e32 v171, v171
	v_rcp_f32_e32 v172, v172
	v_rcp_f32_e32 v173, v173
	s_nop 0
	v_pk_mul_f32 v[166:167], v[166:167], v[222:223]
	v_pk_mul_f32 v[168:169], v[168:169], v[224:225]
	v_pk_mul_f32 v[170:171], v[170:171], v[226:227]
	v_pk_mul_f32 v[172:173], v[172:173], v[228:229]
	v_pk_mul_f32 v[174:175], v[166:167], v[166:167]
	v_pk_fma_f32 v[174:175], v[168:169], v[168:169], v[174:175]
	v_pk_fma_f32 v[174:175], v[170:171], v[170:171], v[174:175]
	v_pk_fma_f32 v[174:175], v[172:173], v[172:173], v[174:175]
	v_cvt_pk_bf16_f32 v230, v166, v167
	v_cvt_pk_bf16_f32 v231, v168, v169
	v_cvt_pk_bf16_f32 v232, v170, v171
	v_cvt_pk_bf16_f32 v233, v172, v173
	global_store_dwordx4 v[160:161], v[230:233], off
	s_nop 1
	s_waitcnt vmcnt(3)
	v_pk_fma_f32 v[166:167], v[4:5], v[164:165], v[184:185] op_sel_hi:[1,0,1]
	v_pk_fma_f32 v[168:169], v[6:7], v[164:165], v[186:187] op_sel_hi:[1,0,1]
	v_pk_fma_f32 v[170:171], v[0:1], v[164:165], v[188:189] op_sel_hi:[1,0,1]
	v_pk_fma_f32 v[172:173], v[2:3], v[164:165], v[190:191] op_sel_hi:[1,0,1]
	v_exp_f32_e32 v166, v166
	v_exp_f32_e32 v167, v167
	v_exp_f32_e32 v168, v168
	v_exp_f32_e32 v169, v169
	v_exp_f32_e32 v170, v170
	v_exp_f32_e32 v171, v171
	v_exp_f32_e32 v172, v172
	v_exp_f32_e32 v173, v173
	v_lshlrev_b32_e32 v222, 16, v204
	v_and_b32_e32 v223, 0xffff0000, v204
	v_lshlrev_b32_e32 v224, 16, v205
	v_and_b32_e32 v225, 0xffff0000, v205
	v_lshlrev_b32_e32 v226, 16, v206
	v_and_b32_e32 v227, 0xffff0000, v206
	v_lshlrev_b32_e32 v228, 16, v207
	v_and_b32_e32 v229, 0xffff0000, v207
	v_pk_add_f32 v[166:167], v[166:167], 1.0 op_sel_hi:[1,0]
	v_pk_add_f32 v[168:169], v[168:169], 1.0 op_sel_hi:[1,0]
	v_pk_add_f32 v[170:171], v[170:171], 1.0 op_sel_hi:[1,0]
	v_pk_add_f32 v[172:173], v[172:173], 1.0 op_sel_hi:[1,0]
	v_rcp_f32_e32 v166, v166
	v_rcp_f32_e32 v167, v167
	v_rcp_f32_e32 v168, v168
	v_rcp_f32_e32 v169, v169
	v_rcp_f32_e32 v170, v170
	v_rcp_f32_e32 v171, v171
	v_rcp_f32_e32 v172, v172
	v_rcp_f32_e32 v173, v173
	s_nop 0
	v_pk_mul_f32 v[166:167], v[166:167], v[222:223]
	v_pk_mul_f32 v[168:169], v[168:169], v[224:225]
	v_pk_mul_f32 v[170:171], v[170:171], v[226:227]
	v_pk_mul_f32 v[172:173], v[172:173], v[228:229]
	v_pk_fma_f32 v[174:175], v[166:167], v[166:167], v[174:175]
	v_pk_fma_f32 v[174:175], v[168:169], v[168:169], v[174:175]
	v_pk_fma_f32 v[174:175], v[170:171], v[170:171], v[174:175]
	v_pk_fma_f32 v[174:175], v[172:173], v[172:173], v[174:175]
	v_cvt_pk_bf16_f32 v230, v166, v167
	v_cvt_pk_bf16_f32 v231, v168, v169
	v_cvt_pk_bf16_f32 v232, v170, v171
	v_cvt_pk_bf16_f32 v233, v172, v173
	global_store_dwordx4 v[160:161], v[230:233], off offset:256
	v_add_f32_e32 v234, v174, v175
	v_mov_b32_e32 v235, v234
	s_nop 1
	v_permlane32_swap_b32 v235, v234
	s_nop 1
	v_add_f32_e32 v234, v234, v235
	v_mov_b32_e32 v235, v234
	s_nop 1
	v_permlane16_swap_b32 v235, v234
	s_nop 1
	v_add_f32_e32 v234, v234, v235
	s_mov_b64 exec, s[46:47]
	global_atomic_add_f32 v[162:163], v234, off offset:704
	s_mov_b64 exec, -1
	s_andn2_b64 vcc, exec, s[44:45]
	s_mov_b64 s[44:45], -1
	s_cbranch_vccnz .LBB0_243
	s_andn2_b64 vcc, exec, s[0:1]
	s_cbranch_vccnz .LBB0_242
	s_barrier
	s_branch .LBB0_242
